# ev_in/odin bf16 staging: second DPP exchange (lane^2) so each lane owns 4 adjacent columns of one row; 16 ds_write_b64 per tile instead of 32 ds_write_b32
# speedup vs baseline: 1.0048x; 1.0009x over previous
.Levin1_notr:
	s_cmp_eq_u32 s24, 2
	s_cbranch_scc1 .LBB0_259
	s_cmp_eq_u32 s24, 7
	s_cbranch_scc1 .LBB0_259
	s_cmp_ge_u32 s24, 3
	s_cselect_b32 s2, 1, 0
	s_sub_u32 s2, s24, s2
	s_cmp_ge_u32 s24, 8
	s_cselect_b32 s3, 1, 0
	s_sub_u32 s2, s2, s3
	s_lshl_b32 s2, s2, 9
	s_add_u32 s2, s2, s0
	s_lshl_b32 s2, s2, 1
	s_mul_i32 s3, s1, 0x1c00
	s_add_u32 s2, s2, s3
	s_add_u32 s98, s90, 0x3971900
	s_addc_u32 s99, s91, 0
	s_add_u32 s98, s98, s2
	s_addc_u32 s99, s99, 0
	v_and_b32_e32 v120, 1, v118
	v_lshlrev_b32_e32 v121, 6, v120
	v_sub_u32_e32 v121, v121, v120
	v_sub_u32_e32 v121, v121, v120
	v_add_u32_e32 v121, v121, v112
	v_cmp_eq_u32_e32 vcc, 1, v120
	v_mov_b32_e32 v120, 0x05040100
	v_mov_b32_e32 v122, 0x03020706
	s_nop 1
	v_cndmask_b32_e32 v120, v120, v122, vcc
	v_and_b32_e32 v122, 2, v118
	v_cmp_ne_u32_e64 s[100:101], 0, v122
	v_and_b32_e32 v121, 3, v118
	v_lshlrev_b32_e32 v121, 6, v121
	v_and_b32_e32 v122, 28, v118
	v_lshl_add_u32 v121, v122, 1, v121
	v_lshrrev_b32_e32 v122, 5, v118
	v_lshl_add_u32 v121, v122, 8, v121
	v_sub_u32_e32 v122, v113, v118
	v_lshlrev_b32_e32 v123, 4, v118
	v_sub_u32_e32 v122, v113, v123
	v_add_u32_e32 v121, v121, v122
	v_cvt_pk_bf16_f32 v64, v48, v49
	v_cvt_pk_bf16_f32 v65, v50, v51
	v_cvt_pk_bf16_f32 v66, v52, v53
	v_cvt_pk_bf16_f32 v67, v54, v55
	v_cvt_pk_bf16_f32 v68, v56, v57
	v_cvt_pk_bf16_f32 v69, v58, v59
	v_cvt_pk_bf16_f32 v70, v60, v61
	v_cvt_pk_bf16_f32 v71, v62, v63
	v_mov_b32_dpp v72, v64 quad_perm:[1,0,3,2] row_mask:0xf bank_mask:0xf
	v_mov_b32_dpp v73, v65 quad_perm:[1,0,3,2] row_mask:0xf bank_mask:0xf
	v_mov_b32_dpp v74, v66 quad_perm:[1,0,3,2] row_mask:0xf bank_mask:0xf
	v_mov_b32_dpp v75, v67 quad_perm:[1,0,3,2] row_mask:0xf bank_mask:0xf
	v_mov_b32_dpp v76, v68 quad_perm:[1,0,3,2] row_mask:0xf bank_mask:0xf
	v_mov_b32_dpp v77, v69 quad_perm:[1,0,3,2] row_mask:0xf bank_mask:0xf
	v_mov_b32_dpp v78, v70 quad_perm:[1,0,3,2] row_mask:0xf bank_mask:0xf
	v_mov_b32_dpp v79, v71 quad_perm:[1,0,3,2] row_mask:0xf bank_mask:0xf
	v_perm_b32 v72, v72, v64, v120
	v_perm_b32 v73, v73, v65, v120
	v_perm_b32 v74, v74, v66, v120
	v_perm_b32 v75, v75, v67, v120
	v_perm_b32 v76, v76, v68, v120
	v_perm_b32 v77, v77, v69, v120
	v_perm_b32 v78, v78, v70, v120
	v_perm_b32 v79, v79, v71, v120
	v_mov_b32_dpp v64, v72 quad_perm:[2,3,0,1] row_mask:0xf bank_mask:0xf
	v_mov_b32_dpp v65, v73 quad_perm:[2,3,0,1] row_mask:0xf bank_mask:0xf
	v_mov_b32_dpp v66, v74 quad_perm:[2,3,0,1] row_mask:0xf bank_mask:0xf
	v_mov_b32_dpp v67, v75 quad_perm:[2,3,0,1] row_mask:0xf bank_mask:0xf
	v_mov_b32_dpp v68, v76 quad_perm:[2,3,0,1] row_mask:0xf bank_mask:0xf
	v_mov_b32_dpp v69, v77 quad_perm:[2,3,0,1] row_mask:0xf bank_mask:0xf
	v_mov_b32_dpp v70, v78 quad_perm:[2,3,0,1] row_mask:0xf bank_mask:0xf
	v_mov_b32_dpp v71, v79 quad_perm:[2,3,0,1] row_mask:0xf bank_mask:0xf
	v_cndmask_b32_e64 v72, v72, v65, s[100:101]
	v_cndmask_b32_e64 v73, v64, v73, s[100:101]
	v_cndmask_b32_e64 v74, v74, v67, s[100:101]
	v_cndmask_b32_e64 v75, v66, v75, s[100:101]
	v_cndmask_b32_e64 v76, v76, v69, s[100:101]
	v_cndmask_b32_e64 v77, v68, v77, s[100:101]
	v_cndmask_b32_e64 v78, v78, v71, s[100:101]
	v_cndmask_b32_e64 v79, v70, v79, s[100:101]
	ds_write_b64 v121, v[72:73]
	ds_write_b64 v121, v[74:75] offset:512
	ds_write_b64 v121, v[76:77] offset:1024
	ds_write_b64 v121, v[78:79] offset:1536
	ds_read_b128 v[80:83], v113
	ds_read_b128 v[84:87], v113 offset:1024
	v_cvt_pk_bf16_f32 v64, v16, v17
	v_cvt_pk_bf16_f32 v65, v18, v19
	v_cvt_pk_bf16_f32 v66, v20, v21
	v_cvt_pk_bf16_f32 v67, v22, v23
	v_cvt_pk_bf16_f32 v68, v24, v25
	v_cvt_pk_bf16_f32 v69, v26, v27
	v_cvt_pk_bf16_f32 v70, v28, v29
	v_cvt_pk_bf16_f32 v71, v30, v31
	v_mov_b32_dpp v72, v64 quad_perm:[1,0,3,2] row_mask:0xf bank_mask:0xf
	v_mov_b32_dpp v73, v65 quad_perm:[1,0,3,2] row_mask:0xf bank_mask:0xf
	v_mov_b32_dpp v74, v66 quad_perm:[1,0,3,2] row_mask:0xf bank_mask:0xf
	v_mov_b32_dpp v75, v67 quad_perm:[1,0,3,2] row_mask:0xf bank_mask:0xf
	v_mov_b32_dpp v76, v68 quad_perm:[1,0,3,2] row_mask:0xf bank_mask:0xf
	v_mov_b32_dpp v77, v69 quad_perm:[1,0,3,2] row_mask:0xf bank_mask:0xf
	v_mov_b32_dpp v78, v70 quad_perm:[1,0,3,2] row_mask:0xf bank_mask:0xf
	v_mov_b32_dpp v79, v71 quad_perm:[1,0,3,2] row_mask:0xf bank_mask:0xf
	v_perm_b32 v72, v72, v64, v120
	v_perm_b32 v73, v73, v65, v120
	v_perm_b32 v74, v74, v66, v120
	v_perm_b32 v75, v75, v67, v120
	v_perm_b32 v76, v76, v68, v120
	v_perm_b32 v77, v77, v69, v120
	v_perm_b32 v78, v78, v70, v120
	v_perm_b32 v79, v79, v71, v120
	v_mov_b32_dpp v64, v72 quad_perm:[2,3,0,1] row_mask:0xf bank_mask:0xf
	v_mov_b32_dpp v65, v73 quad_perm:[2,3,0,1] row_mask:0xf bank_mask:0xf
	v_mov_b32_dpp v66, v74 quad_perm:[2,3,0,1] row_mask:0xf bank_mask:0xf
	v_mov_b32_dpp v67, v75 quad_perm:[2,3,0,1] row_mask:0xf bank_mask:0xf
	v_mov_b32_dpp v68, v76 quad_perm:[2,3,0,1] row_mask:0xf bank_mask:0xf
	v_mov_b32_dpp v69, v77 quad_perm:[2,3,0,1] row_mask:0xf bank_mask:0xf
	v_mov_b32_dpp v70, v78 quad_perm:[2,3,0,1] row_mask:0xf bank_mask:0xf
	v_mov_b32_dpp v71, v79 quad_perm:[2,3,0,1] row_mask:0xf bank_mask:0xf
	v_cndmask_b32_e64 v72, v72, v65, s[100:101]
	v_cndmask_b32_e64 v73, v64, v73, s[100:101]
	v_cndmask_b32_e64 v74, v74, v67, s[100:101]
	v_cndmask_b32_e64 v75, v66, v75, s[100:101]
	v_cndmask_b32_e64 v76, v76, v69, s[100:101]
	v_cndmask_b32_e64 v77, v68, v77, s[100:101]
	v_cndmask_b32_e64 v78, v78, v71, s[100:101]
	v_cndmask_b32_e64 v79, v70, v79, s[100:101]
	ds_write_b64 v121, v[72:73]
	ds_write_b64 v121, v[74:75] offset:512
	ds_write_b64 v121, v[76:77] offset:1024
	ds_write_b64 v121, v[78:79] offset:1536
	ds_read_b128 v[88:91], v113
	ds_read_b128 v[92:95], v113 offset:1024
	v_cvt_pk_bf16_f32 v64, v32, v33
	v_cvt_pk_bf16_f32 v65, v34, v35
	v_cvt_pk_bf16_f32 v66, v36, v37
	v_cvt_pk_bf16_f32 v67, v38, v39
	v_cvt_pk_bf16_f32 v68, v40, v41
	v_cvt_pk_bf16_f32 v69, v42, v43
	v_cvt_pk_bf16_f32 v70, v44, v45
	v_cvt_pk_bf16_f32 v71, v46, v47
	v_mov_b32_dpp v72, v64 quad_perm:[1,0,3,2] row_mask:0xf bank_mask:0xf
	v_mov_b32_dpp v73, v65 quad_perm:[1,0,3,2] row_mask:0xf bank_mask:0xf
	v_mov_b32_dpp v74, v66 quad_perm:[1,0,3,2] row_mask:0xf bank_mask:0xf
	v_mov_b32_dpp v75, v67 quad_perm:[1,0,3,2] row_mask:0xf bank_mask:0xf
	v_mov_b32_dpp v76, v68 quad_perm:[1,0,3,2] row_mask:0xf bank_mask:0xf
	v_mov_b32_dpp v77, v69 quad_perm:[1,0,3,2] row_mask:0xf bank_mask:0xf
	v_mov_b32_dpp v78, v70 quad_perm:[1,0,3,2] row_mask:0xf bank_mask:0xf
	v_mov_b32_dpp v79, v71 quad_perm:[1,0,3,2] row_mask:0xf bank_mask:0xf
	v_perm_b32 v72, v72, v64, v120
	v_perm_b32 v73, v73, v65, v120
	v_perm_b32 v74, v74, v66, v120
	v_perm_b32 v75, v75, v67, v120
	v_perm_b32 v76, v76, v68, v120
	v_perm_b32 v77, v77, v69, v120
	v_perm_b32 v78, v78, v70, v120
	v_perm_b32 v79, v79, v71, v120
	v_mov_b32_dpp v64, v72 quad_perm:[2,3,0,1] row_mask:0xf bank_mask:0xf
	v_mov_b32_dpp v65, v73 quad_perm:[2,3,0,1] row_mask:0xf bank_mask:0xf
	v_mov_b32_dpp v66, v74 quad_perm:[2,3,0,1] row_mask:0xf bank_mask:0xf
	v_mov_b32_dpp v67, v75 quad_perm:[2,3,0,1] row_mask:0xf bank_mask:0xf
	v_mov_b32_dpp v68, v76 quad_perm:[2,3,0,1] row_mask:0xf bank_mask:0xf
	v_mov_b32_dpp v69, v77 quad_perm:[2,3,0,1] row_mask:0xf bank_mask:0xf
	v_mov_b32_dpp v70, v78 quad_perm:[2,3,0,1] row_mask:0xf bank_mask:0xf
	v_mov_b32_dpp v71, v79 quad_perm:[2,3,0,1] row_mask:0xf bank_mask:0xf
	v_cndmask_b32_e64 v72, v72, v65, s[100:101]
	v_cndmask_b32_e64 v73, v64, v73, s[100:101]
	v_cndmask_b32_e64 v74, v74, v67, s[100:101]
	v_cndmask_b32_e64 v75, v66, v75, s[100:101]
	v_cndmask_b32_e64 v76, v76, v69, s[100:101]
	v_cndmask_b32_e64 v77, v68, v77, s[100:101]
	v_cndmask_b32_e64 v78, v78, v71, s[100:101]
	v_cndmask_b32_e64 v79, v70, v79, s[100:101]
	ds_write_b64 v121, v[72:73]
	ds_write_b64 v121, v[74:75] offset:512
	ds_write_b64 v121, v[76:77] offset:1024
	ds_write_b64 v121, v[78:79] offset:1536
	ds_read_b128 v[96:99], v113
	ds_read_b128 v[100:103], v113 offset:1024
	v_cvt_pk_bf16_f32 v64, v0, v1
	v_cvt_pk_bf16_f32 v65, v2, v3
	v_cvt_pk_bf16_f32 v66, v4, v5
	v_cvt_pk_bf16_f32 v67, v6, v7
	v_cvt_pk_bf16_f32 v68, v8, v9
	v_cvt_pk_bf16_f32 v69, v10, v11
	v_cvt_pk_bf16_f32 v70, v12, v13
	v_cvt_pk_bf16_f32 v71, v14, v15
	v_mov_b32_dpp v72, v64 quad_perm:[1,0,3,2] row_mask:0xf bank_mask:0xf
	v_mov_b32_dpp v73, v65 quad_perm:[1,0,3,2] row_mask:0xf bank_mask:0xf
	v_mov_b32_dpp v74, v66 quad_perm:[1,0,3,2] row_mask:0xf bank_mask:0xf
	v_mov_b32_dpp v75, v67 quad_perm:[1,0,3,2] row_mask:0xf bank_mask:0xf
	v_mov_b32_dpp v76, v68 quad_perm:[1,0,3,2] row_mask:0xf bank_mask:0xf
	v_mov_b32_dpp v77, v69 quad_perm:[1,0,3,2] row_mask:0xf bank_mask:0xf
	v_mov_b32_dpp v78, v70 quad_perm:[1,0,3,2] row_mask:0xf bank_mask:0xf
	v_mov_b32_dpp v79, v71 quad_perm:[1,0,3,2] row_mask:0xf bank_mask:0xf
	v_perm_b32 v72, v72, v64, v120
	v_perm_b32 v73, v73, v65, v120
	v_perm_b32 v74, v74, v66, v120
	v_perm_b32 v75, v75, v67, v120
	v_perm_b32 v76, v76, v68, v120
	v_perm_b32 v77, v77, v69, v120
	v_perm_b32 v78, v78, v70, v120
	v_perm_b32 v79, v79, v71, v120
	v_mov_b32_dpp v64, v72 quad_perm:[2,3,0,1] row_mask:0xf bank_mask:0xf
	v_mov_b32_dpp v65, v73 quad_perm:[2,3,0,1] row_mask:0xf bank_mask:0xf
	v_mov_b32_dpp v66, v74 quad_perm:[2,3,0,1] row_mask:0xf bank_mask:0xf
	v_mov_b32_dpp v67, v75 quad_perm:[2,3,0,1] row_mask:0xf bank_mask:0xf
	v_mov_b32_dpp v68, v76 quad_perm:[2,3,0,1] row_mask:0xf bank_mask:0xf
	v_mov_b32_dpp v69, v77 quad_perm:[2,3,0,1] row_mask:0xf bank_mask:0xf
	v_mov_b32_dpp v70, v78 quad_perm:[2,3,0,1] row_mask:0xf bank_mask:0xf
	v_mov_b32_dpp v71, v79 quad_perm:[2,3,0,1] row_mask:0xf bank_mask:0xf
	v_cndmask_b32_e64 v72, v72, v65, s[100:101]
	v_cndmask_b32_e64 v73, v64, v73, s[100:101]
	v_cndmask_b32_e64 v74, v74, v67, s[100:101]
	v_cndmask_b32_e64 v75, v66, v75, s[100:101]
	v_cndmask_b32_e64 v76, v76, v69, s[100:101]
	v_cndmask_b32_e64 v77, v68, v77, s[100:101]
	v_cndmask_b32_e64 v78, v78, v71, s[100:101]
	v_cndmask_b32_e64 v79, v70, v79, s[100:101]
	ds_write_b64 v121, v[72:73]
	ds_write_b64 v121, v[74:75] offset:512
	ds_write_b64 v121, v[76:77] offset:1024
	ds_write_b64 v121, v[78:79] offset:1536
	ds_read_b128 v[104:107], v113
	ds_read_b128 v[108:111], v113 offset:1024
	s_waitcnt lgkmcnt(0)
	global_store_dwordx4 v114, v[80:83], s[98:99]
	s_add_u32 s100, s98, 0x1c000
	s_addc_u32 s101, s99, 0
	global_store_dwordx4 v114, v[84:87], s[100:101]
	global_store_dwordx4 v114, v[88:91], s[98:99] offset:64
	global_store_dwordx4 v114, v[92:95], s[100:101] offset:64
	s_add_u32 s98, s98, 0x38000
	s_addc_u32 s99, s99, 0
	global_store_dwordx4 v114, v[96:99], s[98:99]
	s_add_u32 s100, s98, 0x1c000
	s_addc_u32 s101, s99, 0
	global_store_dwordx4 v114, v[100:103], s[100:101]
	global_store_dwordx4 v114, v[104:107], s[98:99] offset:64
	global_store_dwordx4 v114, v[108:111], s[100:101] offset:64
	s_branch .LBB0_259

.Lodin4_nat:
	s_lshl_b32 s8, s7, 11
	s_add_u32 s8, s8, s9
	s_lshl_b32 s9, s6, 1
	s_add_u32 s8, s8, s9
	s_add_u32 s98, s90, s8
	s_addc_u32 s99, s91, 0
	v_and_b32_e32 v120, 1, v118
	v_lshlrev_b32_e32 v121, 6, v120
	v_sub_u32_e32 v121, v121, v120
	v_sub_u32_e32 v121, v121, v120
	v_add_u32_e32 v121, v121, v112
	v_cmp_eq_u32_e32 vcc, 1, v120
	v_mov_b32_e32 v120, 0x05040100
	v_mov_b32_e32 v122, 0x03020706
	s_nop 1
	v_cndmask_b32_e32 v120, v120, v122, vcc
	v_and_b32_e32 v122, 2, v118
	v_cmp_ne_u32_e64 s[100:101], 0, v122
	v_and_b32_e32 v121, 3, v118
	v_lshlrev_b32_e32 v121, 6, v121
	v_and_b32_e32 v122, 28, v118
	v_lshl_add_u32 v121, v122, 1, v121
	v_lshrrev_b32_e32 v122, 5, v118
	v_lshl_add_u32 v121, v122, 8, v121
	v_sub_u32_e32 v122, v113, v118
	v_lshlrev_b32_e32 v123, 4, v118
	v_sub_u32_e32 v122, v113, v123
	v_add_u32_e32 v121, v121, v122
	v_cvt_pk_bf16_f32 v64, v48, v49
	v_cvt_pk_bf16_f32 v65, v50, v51
	v_cvt_pk_bf16_f32 v66, v52, v53
	v_cvt_pk_bf16_f32 v67, v54, v55
	v_cvt_pk_bf16_f32 v68, v56, v57
	v_cvt_pk_bf16_f32 v69, v58, v59
	v_cvt_pk_bf16_f32 v70, v60, v61
	v_cvt_pk_bf16_f32 v71, v62, v63
	v_mov_b32_dpp v72, v64 quad_perm:[1,0,3,2] row_mask:0xf bank_mask:0xf
	v_mov_b32_dpp v73, v65 quad_perm:[1,0,3,2] row_mask:0xf bank_mask:0xf
	v_mov_b32_dpp v74, v66 quad_perm:[1,0,3,2] row_mask:0xf bank_mask:0xf
	v_mov_b32_dpp v75, v67 quad_perm:[1,0,3,2] row_mask:0xf bank_mask:0xf
	v_mov_b32_dpp v76, v68 quad_perm:[1,0,3,2] row_mask:0xf bank_mask:0xf
	v_mov_b32_dpp v77, v69 quad_perm:[1,0,3,2] row_mask:0xf bank_mask:0xf
	v_mov_b32_dpp v78, v70 quad_perm:[1,0,3,2] row_mask:0xf bank_mask:0xf
	v_mov_b32_dpp v79, v71 quad_perm:[1,0,3,2] row_mask:0xf bank_mask:0xf
	v_perm_b32 v72, v72, v64, v120
	v_perm_b32 v73, v73, v65, v120
	v_perm_b32 v74, v74, v66, v120
	v_perm_b32 v75, v75, v67, v120
	v_perm_b32 v76, v76, v68, v120
	v_perm_b32 v77, v77, v69, v120
	v_perm_b32 v78, v78, v70, v120
	v_perm_b32 v79, v79, v71, v120
	v_mov_b32_dpp v64, v72 quad_perm:[2,3,0,1] row_mask:0xf bank_mask:0xf
	v_mov_b32_dpp v65, v73 quad_perm:[2,3,0,1] row_mask:0xf bank_mask:0xf
	v_mov_b32_dpp v66, v74 quad_perm:[2,3,0,1] row_mask:0xf bank_mask:0xf
	v_mov_b32_dpp v67, v75 quad_perm:[2,3,0,1] row_mask:0xf bank_mask:0xf
	v_mov_b32_dpp v68, v76 quad_perm:[2,3,0,1] row_mask:0xf bank_mask:0xf
	v_mov_b32_dpp v69, v77 quad_perm:[2,3,0,1] row_mask:0xf bank_mask:0xf
	v_mov_b32_dpp v70, v78 quad_perm:[2,3,0,1] row_mask:0xf bank_mask:0xf
	v_mov_b32_dpp v71, v79 quad_perm:[2,3,0,1] row_mask:0xf bank_mask:0xf
	v_cndmask_b32_e64 v72, v72, v65, s[100:101]
	v_cndmask_b32_e64 v73, v64, v73, s[100:101]
	v_cndmask_b32_e64 v74, v74, v67, s[100:101]
	v_cndmask_b32_e64 v75, v66, v75, s[100:101]
	v_cndmask_b32_e64 v76, v76, v69, s[100:101]
	v_cndmask_b32_e64 v77, v68, v77, s[100:101]
	v_cndmask_b32_e64 v78, v78, v71, s[100:101]
	v_cndmask_b32_e64 v79, v70, v79, s[100:101]
	ds_write_b64 v121, v[72:73]
	ds_write_b64 v121, v[74:75] offset:512
	ds_write_b64 v121, v[76:77] offset:1024
	ds_write_b64 v121, v[78:79] offset:1536
	ds_read_b128 v[80:83], v113
	ds_read_b128 v[84:87], v113 offset:1024
	v_cvt_pk_bf16_f32 v64, v16, v17
	v_cvt_pk_bf16_f32 v65, v18, v19
	v_cvt_pk_bf16_f32 v66, v20, v21
	v_cvt_pk_bf16_f32 v67, v22, v23
	v_cvt_pk_bf16_f32 v68, v24, v25
	v_cvt_pk_bf16_f32 v69, v26, v27
	v_cvt_pk_bf16_f32 v70, v28, v29
	v_cvt_pk_bf16_f32 v71, v30, v31
	v_mov_b32_dpp v72, v64 quad_perm:[1,0,3,2] row_mask:0xf bank_mask:0xf
	v_mov_b32_dpp v73, v65 quad_perm:[1,0,3,2] row_mask:0xf bank_mask:0xf
	v_mov_b32_dpp v74, v66 quad_perm:[1,0,3,2] row_mask:0xf bank_mask:0xf
	v_mov_b32_dpp v75, v67 quad_perm:[1,0,3,2] row_mask:0xf bank_mask:0xf
	v_mov_b32_dpp v76, v68 quad_perm:[1,0,3,2] row_mask:0xf bank_mask:0xf
	v_mov_b32_dpp v77, v69 quad_perm:[1,0,3,2] row_mask:0xf bank_mask:0xf
	v_mov_b32_dpp v78, v70 quad_perm:[1,0,3,2] row_mask:0xf bank_mask:0xf
	v_mov_b32_dpp v79, v71 quad_perm:[1,0,3,2] row_mask:0xf bank_mask:0xf
	v_perm_b32 v72, v72, v64, v120
	v_perm_b32 v73, v73, v65, v120
	v_perm_b32 v74, v74, v66, v120
	v_perm_b32 v75, v75, v67, v120
	v_perm_b32 v76, v76, v68, v120
	v_perm_b32 v77, v77, v69, v120
	v_perm_b32 v78, v78, v70, v120
	v_perm_b32 v79, v79, v71, v120
	v_mov_b32_dpp v64, v72 quad_perm:[2,3,0,1] row_mask:0xf bank_mask:0xf
	v_mov_b32_dpp v65, v73 quad_perm:[2,3,0,1] row_mask:0xf bank_mask:0xf
	v_mov_b32_dpp v66, v74 quad_perm:[2,3,0,1] row_mask:0xf bank_mask:0xf
	v_mov_b32_dpp v67, v75 quad_perm:[2,3,0,1] row_mask:0xf bank_mask:0xf
	v_mov_b32_dpp v68, v76 quad_perm:[2,3,0,1] row_mask:0xf bank_mask:0xf
	v_mov_b32_dpp v69, v77 quad_perm:[2,3,0,1] row_mask:0xf bank_mask:0xf
	v_mov_b32_dpp v70, v78 quad_perm:[2,3,0,1] row_mask:0xf bank_mask:0xf
	v_mov_b32_dpp v71, v79 quad_perm:[2,3,0,1] row_mask:0xf bank_mask:0xf
	v_cndmask_b32_e64 v72, v72, v65, s[100:101]
	v_cndmask_b32_e64 v73, v64, v73, s[100:101]
	v_cndmask_b32_e64 v74, v74, v67, s[100:101]
	v_cndmask_b32_e64 v75, v66, v75, s[100:101]
	v_cndmask_b32_e64 v76, v76, v69, s[100:101]
	v_cndmask_b32_e64 v77, v68, v77, s[100:101]
	v_cndmask_b32_e64 v78, v78, v71, s[100:101]
	v_cndmask_b32_e64 v79, v70, v79, s[100:101]
	ds_write_b64 v121, v[72:73]
	ds_write_b64 v121, v[74:75] offset:512
	ds_write_b64 v121, v[76:77] offset:1024
	ds_write_b64 v121, v[78:79] offset:1536
	ds_read_b128 v[88:91], v113
	ds_read_b128 v[92:95], v113 offset:1024
	v_cvt_pk_bf16_f32 v64, v32, v33
	v_cvt_pk_bf16_f32 v65, v34, v35
	v_cvt_pk_bf16_f32 v66, v36, v37
	v_cvt_pk_bf16_f32 v67, v38, v39
	v_cvt_pk_bf16_f32 v68, v40, v41
	v_cvt_pk_bf16_f32 v69, v42, v43
	v_cvt_pk_bf16_f32 v70, v44, v45
	v_cvt_pk_bf16_f32 v71, v46, v47
	v_mov_b32_dpp v72, v64 quad_perm:[1,0,3,2] row_mask:0xf bank_mask:0xf
	v_mov_b32_dpp v73, v65 quad_perm:[1,0,3,2] row_mask:0xf bank_mask:0xf
	v_mov_b32_dpp v74, v66 quad_perm:[1,0,3,2] row_mask:0xf bank_mask:0xf
	v_mov_b32_dpp v75, v67 quad_perm:[1,0,3,2] row_mask:0xf bank_mask:0xf
	v_mov_b32_dpp v76, v68 quad_perm:[1,0,3,2] row_mask:0xf bank_mask:0xf
	v_mov_b32_dpp v77, v69 quad_perm:[1,0,3,2] row_mask:0xf bank_mask:0xf
	v_mov_b32_dpp v78, v70 quad_perm:[1,0,3,2] row_mask:0xf bank_mask:0xf
	v_mov_b32_dpp v79, v71 quad_perm:[1,0,3,2] row_mask:0xf bank_mask:0xf
	v_perm_b32 v72, v72, v64, v120
	v_perm_b32 v73, v73, v65, v120
	v_perm_b32 v74, v74, v66, v120
	v_perm_b32 v75, v75, v67, v120
	v_perm_b32 v76, v76, v68, v120
	v_perm_b32 v77, v77, v69, v120
	v_perm_b32 v78, v78, v70, v120
	v_perm_b32 v79, v79, v71, v120
	v_mov_b32_dpp v64, v72 quad_perm:[2,3,0,1] row_mask:0xf bank_mask:0xf
	v_mov_b32_dpp v65, v73 quad_perm:[2,3,0,1] row_mask:0xf bank_mask:0xf
	v_mov_b32_dpp v66, v74 quad_perm:[2,3,0,1] row_mask:0xf bank_mask:0xf
	v_mov_b32_dpp v67, v75 quad_perm:[2,3,0,1] row_mask:0xf bank_mask:0xf
	v_mov_b32_dpp v68, v76 quad_perm:[2,3,0,1] row_mask:0xf bank_mask:0xf
	v_mov_b32_dpp v69, v77 quad_perm:[2,3,0,1] row_mask:0xf bank_mask:0xf
	v_mov_b32_dpp v70, v78 quad_perm:[2,3,0,1] row_mask:0xf bank_mask:0xf
	v_mov_b32_dpp v71, v79 quad_perm:[2,3,0,1] row_mask:0xf bank_mask:0xf
	v_cndmask_b32_e64 v72, v72, v65, s[100:101]
	v_cndmask_b32_e64 v73, v64, v73, s[100:101]
	v_cndmask_b32_e64 v74, v74, v67, s[100:101]
	v_cndmask_b32_e64 v75, v66, v75, s[100:101]
	v_cndmask_b32_e64 v76, v76, v69, s[100:101]
	v_cndmask_b32_e64 v77, v68, v77, s[100:101]
	v_cndmask_b32_e64 v78, v78, v71, s[100:101]
	v_cndmask_b32_e64 v79, v70, v79, s[100:101]
	ds_write_b64 v121, v[72:73]
	ds_write_b64 v121, v[74:75] offset:512
	ds_write_b64 v121, v[76:77] offset:1024
	ds_write_b64 v121, v[78:79] offset:1536
	ds_read_b128 v[96:99], v113
	ds_read_b128 v[100:103], v113 offset:1024
	v_cvt_pk_bf16_f32 v64, v0, v1
	v_cvt_pk_bf16_f32 v65, v2, v3
	v_cvt_pk_bf16_f32 v66, v4, v5
	v_cvt_pk_bf16_f32 v67, v6, v7
	v_cvt_pk_bf16_f32 v68, v8, v9
	v_cvt_pk_bf16_f32 v69, v10, v11
	v_cvt_pk_bf16_f32 v70, v12, v13
	v_cvt_pk_bf16_f32 v71, v14, v15
	v_mov_b32_dpp v72, v64 quad_perm:[1,0,3,2] row_mask:0xf bank_mask:0xf
	v_mov_b32_dpp v73, v65 quad_perm:[1,0,3,2] row_mask:0xf bank_mask:0xf
	v_mov_b32_dpp v74, v66 quad_perm:[1,0,3,2] row_mask:0xf bank_mask:0xf
	v_mov_b32_dpp v75, v67 quad_perm:[1,0,3,2] row_mask:0xf bank_mask:0xf
	v_mov_b32_dpp v76, v68 quad_perm:[1,0,3,2] row_mask:0xf bank_mask:0xf
	v_mov_b32_dpp v77, v69 quad_perm:[1,0,3,2] row_mask:0xf bank_mask:0xf
	v_mov_b32_dpp v78, v70 quad_perm:[1,0,3,2] row_mask:0xf bank_mask:0xf
	v_mov_b32_dpp v79, v71 quad_perm:[1,0,3,2] row_mask:0xf bank_mask:0xf
	v_perm_b32 v72, v72, v64, v120
	v_perm_b32 v73, v73, v65, v120
	v_perm_b32 v74, v74, v66, v120
	v_perm_b32 v75, v75, v67, v120
	v_perm_b32 v76, v76, v68, v120
	v_perm_b32 v77, v77, v69, v120
	v_perm_b32 v78, v78, v70, v120
	v_perm_b32 v79, v79, v71, v120
	v_mov_b32_dpp v64, v72 quad_perm:[2,3,0,1] row_mask:0xf bank_mask:0xf
	v_mov_b32_dpp v65, v73 quad_perm:[2,3,0,1] row_mask:0xf bank_mask:0xf
	v_mov_b32_dpp v66, v74 quad_perm:[2,3,0,1] row_mask:0xf bank_mask:0xf
	v_mov_b32_dpp v67, v75 quad_perm:[2,3,0,1] row_mask:0xf bank_mask:0xf
	v_mov_b32_dpp v68, v76 quad_perm:[2,3,0,1] row_mask:0xf bank_mask:0xf
	v_mov_b32_dpp v69, v77 quad_perm:[2,3,0,1] row_mask:0xf bank_mask:0xf
	v_mov_b32_dpp v70, v78 quad_perm:[2,3,0,1] row_mask:0xf bank_mask:0xf
	v_mov_b32_dpp v71, v79 quad_perm:[2,3,0,1] row_mask:0xf bank_mask:0xf
	v_cndmask_b32_e64 v72, v72, v65, s[100:101]
	v_cndmask_b32_e64 v73, v64, v73, s[100:101]
	v_cndmask_b32_e64 v74, v74, v67, s[100:101]
	v_cndmask_b32_e64 v75, v66, v75, s[100:101]
	v_cndmask_b32_e64 v76, v76, v69, s[100:101]
	v_cndmask_b32_e64 v77, v68, v77, s[100:101]
	v_cndmask_b32_e64 v78, v78, v71, s[100:101]
	v_cndmask_b32_e64 v79, v70, v79, s[100:101]
	ds_write_b64 v121, v[72:73]
	ds_write_b64 v121, v[74:75] offset:512
	ds_write_b64 v121, v[76:77] offset:1024
	ds_write_b64 v121, v[78:79] offset:1536
	ds_read_b128 v[104:107], v113
	ds_read_b128 v[108:111], v113 offset:1024
	s_waitcnt lgkmcnt(0)
	global_store_dwordx4 v114, v[80:83], s[98:99]
	s_add_u32 s100, s98, 0x8000
	s_addc_u32 s101, s99, 0
	global_store_dwordx4 v114, v[84:87], s[100:101]
	global_store_dwordx4 v114, v[88:91], s[98:99] offset:64
	global_store_dwordx4 v114, v[92:95], s[100:101] offset:64
	s_add_u32 s98, s98, 0x10000
	s_addc_u32 s99, s99, 0
	global_store_dwordx4 v114, v[96:99], s[98:99]
	s_add_u32 s100, s98, 0x8000
	s_addc_u32 s101, s99, 0
	global_store_dwordx4 v114, v[100:103], s[100:101]
	global_store_dwordx4 v114, v[104:107], s[98:99] offset:64
	global_store_dwordx4 v114, v[108:111], s[100:101] offset:64
	s_branch .Lodin4_next
